# v37: v36 + P5 state-load waits hoisted in front of the sub-chunk loop; second gate load waited at its first use
# speedup vs baseline: 1.0082x; 1.0074x over previous
; #define LAS __attribute__((address_space(3)))
; DI unsigned pk2(float lo, float hi) { f32x2 v = {lo, hi}; bfv2 b = __builtin_convertvector(v, bfv2); return __builtin_bit_cast(unsigned, b); }
; DI bf16_t f2bf(float x) { return (bf16_t)(pk2(x, 0.f) & 0xffffu); }
; #define MFMA16(a, b, c) __builtin_amdgcn_mfma_f32_16x16x32_bf16((a), (b), (c), 0, 0, 0)
; template <bool OUT> DI void hgrn_item(LAS unsigned char* lds, bf16_t* proj, float* hst, float* hdv, const float* normw, int item, bool dry) {
;     ...
;                 for (int r = 0; r < 4; ++r) { const int tt = 16 * ti + 4 * rq + r, ss = 16 * sj + e16; Ab[tt * TP + ss] = (sj <= ti && ss <= tt) ? f2bf(a[r]) : (bf16_t)0; }
;             }
; #pragma unroll
;             for (int ti = 0; ti < 4; ++ti) { o[ti] = (f32x4){0.f, 0.f, 0.f, 0.f};
; #pragma unroll
;                 for (int ks = 0; ks < 4; ++ks) { const LAS bf16_t* qp = Qt + (16 * ti + e16) * QP + 32 * ks + 4 * rq; const u32x2 q0 = *(const LAS u32x2*)qp, q1 = *(const LAS u32x2*)(qp + 16);
;                     u32x4 qa = {q0.x, q0.y, q1.x, q1.y};
;                     u32x4 sb; sb.x = pk2(st[2 * ks][0], st[2 * ks][1]); sb.y = pk2(st[2 * ks][2], st[2 * ks][3]); sb.z = pk2(st[2 * ks + 1][0], st[2 * ks + 1][1]); sb.w = pk2(st[2 * ks + 1][2], st[2 * ks + 1][3]);
;                     o[ti] = MFMA16(__builtin_bit_cast(bf16x8, qa), __builtin_bit_cast(bf16x8, sb), o[ti]); } }
.LBB0_1170:
	v_or_b32_e32 v56, s14, v104
	v_cmp_gt_u32_e32 vcc, v120, v56
	s_or_b64 s[36:37], s[20:21], vcc
	s_nop 3
	v_cvt_pk_bf16_f32 v50, v50, s0
	v_cndmask_b32_e64 v50, v50, 0, s[36:37]
	v_mad_u64_u32 v[54:55], s[36:37], v56, s39, v[92:93]
	ds_write_b16 v54, v50
	v_or_b32_e32 v50, 1, v56
	v_cmp_gt_u32_e32 vcc, v120, v50
	s_or_b64 s[36:37], s[20:21], vcc
	v_cvt_pk_bf16_f32 v50, v51, s0
	v_cndmask_b32_e64 v50, v50, 0, s[36:37]
	ds_write_b16 v54, v50 offset:144
	v_or_b32_e32 v50, 2, v56
	v_cmp_gt_u32_e32 vcc, v120, v50
	s_or_b64 s[36:37], s[20:21], vcc
	v_cvt_pk_bf16_f32 v50, v52, s0
	v_cndmask_b32_e64 v50, v50, 0, s[36:37]
	ds_write_b16 v54, v50 offset:288
	v_or_b32_e32 v50, 3, v56
	v_cmp_gt_u32_e32 vcc, v120, v50
	s_or_b64 s[36:37], s[20:21], vcc
	v_cvt_pk_bf16_f32 v50, v53, s0
	v_cndmask_b32_e64 v50, v50, 0, s[36:37]
	ds_write_b16 v54, v50 offset:432
	ds_read2_b64 v[50:53], v115 offset1:4
	ds_read2_b64 v[54:57], v115 offset0:8 offset1:12
	v_cvt_pk_bf16_f32 v66, v6, v7
	v_cvt_pk_bf16_f32 v67, v8, v9
	v_cvt_pk_bf16_f32 v68, v10, v11
	v_cvt_pk_bf16_f32 v69, v12, v13
	v_cvt_pk_bf16_f32 v70, v2, v3
	v_cvt_pk_bf16_f32 v71, v4, v5
	s_waitcnt lgkmcnt(1)
	v_mfma_f32_16x16x32_bf16 v[50:53], v[50:53], v[66:69], 0
	v_cvt_pk_bf16_f32 v72, v18, v19
	v_cvt_pk_bf16_f32 v73, v20, v21
	v_cvt_pk_bf16_f32 v100, v14, v15
	v_cvt_pk_bf16_f32 v101, v16, v17
	s_waitcnt lgkmcnt(0)
	v_mfma_f32_16x16x32_bf16 v[50:53], v[54:57], v[70:73], v[50:53]
	ds_read2_b64 v[54:57], v115 offset0:16 offset1:20
	v_cvt_pk_bf16_f32 v102, v26, v27
	v_cvt_pk_bf16_f32 v103, v28, v29
	v_cvt_pk_bf16_f32 v144, v22, v23
	v_cvt_pk_bf16_f32 v145, v24, v25
	s_waitcnt lgkmcnt(0)
	v_mfma_f32_16x16x32_bf16 v[50:53], v[54:57], v[100:103], v[50:53]
	ds_read2_b64 v[54:57], v115 offset0:24 offset1:28
	v_cvt_pk_bf16_f32 v146, v30, v31
	v_cvt_pk_bf16_f32 v147, v32, v33
	v_lshl_add_u64 v[240:241], v[98:99], 0, s[34:35]
	v_add_co_u32_e32 v240, vcc, s47, v240
	s_nop 0
	v_addc_co_u32_e32 v241, vcc, 0, v241, vcc
	global_load_dwordx4 v[244:247], v[240:241], off offset:512
	v_add_u32_e32 v62, 0x1000, v115
	ds_read2_b64 v[58:61], v62 offset0:40 offset1:44
	s_waitcnt lgkmcnt(1)
	v_mfma_f32_16x16x32_bf16 v[54:57], v[54:57], v[144:147], v[50:53]
	s_nop 2
	ds_read2_b64 v[50:53], v62 offset0:32 offset1:36
	v_add_u32_e32 v143, 0x2000, v115
	s_waitcnt lgkmcnt(0)
	v_mfma_f32_16x16x32_bf16 v[50:53], v[50:53], v[66:69], 0
	v_mfma_f32_16x16x32_bf16 v[50:53], v[58:61], v[70:73], v[50:53]
	ds_read2_b64 v[58:61], v62 offset0:48 offset1:52
	s_waitcnt lgkmcnt(0)
	v_mfma_f32_16x16x32_bf16 v[50:53], v[58:61], v[100:103], v[50:53]
	ds_read2_b64 v[58:61], v62 offset0:56 offset1:60
	ds_read2_b64 v[62:65], v143 offset0:72 offset1:76
	s_waitcnt lgkmcnt(1)
	v_mfma_f32_16x16x32_bf16 v[58:61], v[58:61], v[144:147], v[50:53]
	s_nop 3
	ds_read2_b64 v[50:53], v143 offset0:64 offset1:68
	s_waitcnt lgkmcnt(0)
	v_mfma_f32_16x16x32_bf16 v[50:53], v[50:53], v[66:69], 0
	v_mfma_f32_16x16x32_bf16 v[50:53], v[62:65], v[70:73], v[50:53]
	ds_read2_b64 v[62:65], v143 offset0:80 offset1:84
	s_waitcnt lgkmcnt(0)
	v_mfma_f32_16x16x32_bf16 v[50:53], v[62:65], v[100:103], v[50:53]
	ds_read2_b64 v[62:65], v143 offset0:88 offset1:92
	v_add_u32_e32 v143, 0x3000, v115
	s_waitcnt lgkmcnt(0)
	v_mfma_f32_16x16x32_bf16 v[62:65], v[62:65], v[144:147], v[50:53]
	s_nop 3
	ds_read2_b64 v[50:53], v143 offset0:96 offset1:100
	s_waitcnt lgkmcnt(0)
	v_mfma_f32_16x16x32_bf16 v[50:53], v[50:53], v[66:69], 0
	ds_read2_b64 v[66:69], v143 offset0:104 offset1:108
	s_waitcnt lgkmcnt(0)
	v_mfma_f32_16x16x32_bf16 v[50:53], v[66:69], v[70:73], v[50:53]
	ds_read2_b64 v[66:69], v143 offset0:112 offset1:116
	s_waitcnt lgkmcnt(0)
	v_mfma_f32_16x16x32_bf16 v[50:53], v[66:69], v[100:103], v[50:53]
	ds_read2_b64 v[66:69], v143 offset0:120 offset1:124
	v_lshl_add_u64 v[102:103], v[98:99], 0, s[34:35]
	v_lshl_add_u64 v[100:101], v[96:97], 0, s[34:35]
	s_waitcnt lgkmcnt(0)
	v_mfma_f32_16x16x32_bf16 v[70:73], v[66:69], v[144:147], v[50:53]
	v_add_u32_e32 v66, v93, v108
	s_nop 1
	v_add_u32_e32 v67, 0x13c00, v93
	ds_read_b128 v[50:53], v66 offset:34816
	ds_read_b128 v[162:165], v66 offset:34880
	ds_read_b128 v[166:169], v67
	s_add_u32 s34, s34, 0xc8000
	s_addc_u32 s35, s35, 0
	s_cmp_lg_u32 s34, 0x320000
	ds_read_b128 v[170:173], v66 offset:37120
	ds_read_b128 v[174:177], v66 offset:37184
	ds_read_b128 v[178:181], v67 offset:64
	s_waitcnt lgkmcnt(3)
	v_mfma_f32_16x16x32_bf16 v[6:9], v[50:53], v[46:49], v[6:9]
	v_mfma_f32_16x16x32_bf16 v[6:9], v[162:165], v[42:45], v[6:9]
	s_nop 7
	v_pk_mul_f32 v[8:9], v[8:9], v[168:169]
	v_pk_mul_f32 v[6:7], v[6:7], v[166:167]
	ds_read_b128 v[50:53], v66 offset:39424
	ds_read_b128 v[162:165], v66 offset:39488
	ds_read_b128 v[166:169], v67 offset:128
	s_waitcnt lgkmcnt(3)
	v_mfma_f32_16x16x32_bf16 v[10:13], v[170:173], v[46:49], v[10:13]
	v_mfma_f32_16x16x32_bf16 v[10:13], v[174:177], v[42:45], v[10:13]
	s_nop 7
	v_pk_mul_f32 v[12:13], v[12:13], v[180:181]
	v_pk_mul_f32 v[10:11], v[10:11], v[178:179]
	ds_read_b128 v[170:173], v66 offset:41728
	ds_read_b128 v[174:177], v66 offset:41792
	ds_read_b128 v[178:181], v67 offset:192
	s_waitcnt lgkmcnt(3)
	v_mfma_f32_16x16x32_bf16 v[2:5], v[50:53], v[46:49], v[2:5]
	v_mfma_f32_16x16x32_bf16 v[2:5], v[162:165], v[42:45], v[2:5]
	s_nop 7
	v_pk_mul_f32 v[4:5], v[4:5], v[168:169]
	v_pk_mul_f32 v[2:3], v[2:3], v[166:167]
	ds_read_b128 v[50:53], v66 offset:44032
	ds_read_b128 v[162:165], v66 offset:44096
	ds_read_b128 v[166:169], v67 offset:256
	s_waitcnt lgkmcnt(3)
; #define LAS __attribute__((address_space(3)))
; #define MFMA16(a, b, c) __builtin_amdgcn_mfma_f32_16x16x32_bf16((a), (b), (c), 0, 0, 0)
; template <bool OUT> DI void hgrn_item(LAS unsigned char* lds, bf16_t* proj, float* hst, float* hdv, const float* normw, int item, bool dry) {
;     ...
;         for (int dt = 0; dt < 8; ++dt) {
; #pragma unroll
;             for (int ks = 0; ks < 2; ++ks) { const bf16x8 ka = *(const LAS bf16x8*)(KtT + (16 * dt + e16) * TP + 32 * ks + 8 * rq); st[dt] = MFMA16(ka, vfr[ks], st[dt]); }
;             const f32x4 dv = *(const LAS f32x4*)(Dv + 16 * dt + 4 * rq);
;             st[dt] *= dv;
;         }
;         u32x4 gate8[2];
;         if (OUT) {
; #pragma unroll
;             for (int j = 0; j < 2; ++j) { const int cch = tid + 512 * j; gate8[j] = *(const u32x4*)(proj + (row0 + (cch >> 4)) * NPJ + C_HG + h * 128 + 8 * (cch & 15)); }
;         }
;         __syncthreads();
;         if (OUT) {
; #pragma unroll
;             for (int ti = 0; ti < 4; ++ti)
; #pragma unroll
;                 for (int ks = 0; ks < 2; ++ks) if (2 * ks <= ti) { const bf16x8 aa = *(const LAS bf16x8*)(Ab + (16 * ti + e16) * TP + 32 * ks + 8 * rq); o[ti] = MFMA16(aa, vfr[ks], o[ti]); }
;             LAS float* Ob = (LAS float*)(lds + HOB_OFF);
; #pragma unroll
;             for (int ti = 0; ti < 4; ++ti)
; #pragma unroll
;                 for (int r = 0; r < 4; ++r) Ob[(16 * ti + 4 * rq + r) * OBP + w * 16 + e16] = o[ti][r];
	v_mfma_f32_16x16x32_bf16 v[18:21], v[170:173], v[46:49], v[18:21]
	v_mfma_f32_16x16x32_bf16 v[18:21], v[174:177], v[42:45], v[18:21]
	s_nop 7
	v_pk_mul_f32 v[20:21], v[20:21], v[180:181]
	v_pk_mul_f32 v[18:19], v[18:19], v[178:179]
	ds_read_b128 v[170:173], v66 offset:46336
	ds_read_b128 v[174:177], v66 offset:46400
	ds_read_b128 v[178:181], v67 offset:320
	s_waitcnt lgkmcnt(3)
	v_mfma_f32_16x16x32_bf16 v[14:17], v[50:53], v[46:49], v[14:17]
	v_mfma_f32_16x16x32_bf16 v[14:17], v[162:165], v[42:45], v[14:17]
	s_nop 7
	v_pk_mul_f32 v[16:17], v[16:17], v[168:169]
	v_pk_mul_f32 v[14:15], v[14:15], v[166:167]
	ds_read_b128 v[50:53], v66 offset:48640
	ds_read_b128 v[162:165], v66 offset:48704
	ds_read_b128 v[166:169], v67 offset:384
	s_waitcnt lgkmcnt(3)
	v_mfma_f32_16x16x32_bf16 v[26:29], v[170:173], v[46:49], v[26:29]
	v_mfma_f32_16x16x32_bf16 v[26:29], v[174:177], v[42:45], v[26:29]
	s_nop 7
	v_pk_mul_f32 v[28:29], v[28:29], v[180:181]
	v_pk_mul_f32 v[26:27], v[26:27], v[178:179]
	ds_read_b128 v[170:173], v66 offset:50944
	ds_read_b128 v[174:177], v66 offset:51008
	ds_read_b128 v[178:181], v67 offset:448
	s_waitcnt lgkmcnt(3)
	v_mfma_f32_16x16x32_bf16 v[22:25], v[50:53], v[46:49], v[22:25]
	v_mfma_f32_16x16x32_bf16 v[22:25], v[162:165], v[42:45], v[22:25]
	s_nop 7
	v_pk_mul_f32 v[24:25], v[24:25], v[168:169]
	v_pk_mul_f32 v[22:23], v[22:23], v[166:167]
	s_waitcnt lgkmcnt(0)
	v_mfma_f32_16x16x32_bf16 v[30:33], v[170:173], v[46:49], v[30:33]
	v_mfma_f32_16x16x32_bf16 v[30:33], v[174:177], v[42:45], v[30:33]
	s_nop 7
	v_pk_mul_f32 v[32:33], v[32:33], v[180:181]
	v_pk_mul_f32 v[30:31], v[30:31], v[178:179]
	v_add_co_u32_e32 v50, vcc, s47, v100
	s_nop 1
	v_addc_co_u32_e32 v51, vcc, 0, v101, vcc
	global_load_dwordx4 v[50:53], v[50:51], off offset:512
	s_barrier
	ds_read_b128 v[144:147], v116
	ds_read_b128 v[162:165], v116 offset:2304
	ds_read_b128 v[166:169], v116 offset:4608
	ds_read_b128 v[170:173], v116 offset:4672
	ds_read_b128 v[174:177], v116 offset:6912
	ds_read_b128 v[178:181], v116 offset:6976
	s_waitcnt lgkmcnt(5)
	v_mfma_f32_16x16x32_bf16 v[54:57], v[144:147], v[46:49], v[54:57]
	s_waitcnt lgkmcnt(4)
	v_mfma_f32_16x16x32_bf16 v[58:61], v[162:165], v[46:49], v[58:61]
	s_waitcnt lgkmcnt(3)
	v_mfma_f32_16x16x32_bf16 v[62:65], v[166:169], v[46:49], v[62:65]
	s_waitcnt lgkmcnt(2)
	v_mfma_f32_16x16x32_bf16 v[62:65], v[170:173], v[42:45], v[62:65]
	s_waitcnt lgkmcnt(1)
	v_mfma_f32_16x16x32_bf16 v[46:49], v[174:177], v[46:49], v[70:73]
	s_nop 2
	ds_write2_b32 v125, v54, v55 offset1:132
	s_waitcnt lgkmcnt(1)
	v_mfma_f32_16x16x32_bf16 v[42:45], v[178:181], v[42:45], v[46:49]
	s_nop 2
	v_add_u32_e32 v46, 0x400, v125
	ds_write2_b32 v46, v56, v57 offset0:8 offset1:140
	v_add_u32_e32 v46, 0x2000, v125
	ds_write2_b32 v46, v58, v59 offset0:64 offset1:196
	v_add_u32_e32 v46, 0x2400, v125
	ds_write2_b32 v46, v60, v61 offset0:72 offset1:204
	v_add_u32_e32 v46, 0x4200, v125
	ds_write2_b32 v46, v62, v63 offset1:132
	v_add_u32_e32 v46, 0x4600, v125
	ds_write2_b32 v46, v64, v65 offset0:8 offset1:140
	v_add_u32_e32 v46, 0x6200, v125
	ds_write2_b32 v46, v42, v43 offset0:64 offset1:196
	v_add_u32_e32 v42, 0x6600, v125
	ds_write2_b32 v42, v44, v45 offset0:72 offset1:204
	s_waitcnt lgkmcnt(0)
	s_barrier
; #define LAS __attribute__((address_space(3)))
; DI float bflo(unsigned w) { return __uint_as_float(w << 16); }
; DI float bfhi(unsigned w) { return __uint_as_float(w & 0xffff0000u); }
; DI u32x4 pack8(f32x4 a, f32x4 b) { u32x4 w; w.x = pk2(a[0], a[1]); w.y = pk2(a[2], a[3]); w.z = pk2(b[0], b[1]); w.w = pk2(b[2], b[3]); return w; }
; template <bool OUT> DI void hgrn_item(LAS unsigned char* lds, bf16_t* proj, float* hst, float* hdv, const float* normw, int item, bool dry) {
;     ...
; #pragma unroll
;             for (int j = 0; j < 2; ++j) { const int cch = tid + 512 * j, tt = cch >> 4, e0 = 8 * (cch & 15);
;                 const f32x4 a0 = *(const LAS f32x4*)(Ob + tt * OBP + e0), a1 = *(const LAS f32x4*)(Ob + tt * OBP + e0 + 4);
;                 float q = (a0[0] * a0[0] + a0[1] * a0[1]) + (a0[2] * a0[2] + a0[3] * a0[3]) + (a1[0] * a1[0] + a1[1] * a1[1]) + (a1[2] * a1[2] + a1[3] * a1[3]);
;                 q += __shfl_xor(q, 1); q += __shfl_xor(q, 2); q += __shfl_xor(q, 4); q += __shfl_xor(q, 8);
;                 const float rs = __builtin_amdgcn_rsqf(q * (1.0f / 128.0f) + 1e-6f);
;                 const f32x4 n0 = *(const f32x4*)(normw + e0), n1 = *(const f32x4*)(normw + e0 + 4); const u32x4 g = gate8[j];
;                 f32x4 y0, y1;
;                 y0[0] = a0[0] * rs * n0[0] * bflo(g.x); y0[1] = a0[1] * rs * n0[1] * bfhi(g.x); y0[2] = a0[2] * rs * n0[2] * bflo(g.y); y0[3] = a0[3] * rs * n0[3] * bfhi(g.y);
;                 y1[0] = a1[0] * rs * n1[0] * bflo(g.z); y1[1] = a1[1] * rs * n1[1] * bfhi(g.z); y1[2] = a1[2] * rs * n1[2] * bflo(g.w); y1[3] = a1[3] * rs * n1[3] * bfhi(g.w);
;                 if (!dry) *(u32x4*)(proj + (row0 + tt) * NPJ + C_HQ + h * 128 + e0) = pack8(y0, y1); }
	ds_read_b128 v[42:45], v117
	ds_read_b128 v[46:49], v117 offset:16
	s_waitcnt vmcnt(1)
	v_lshlrev_b32_e32 v64, 16, v246
	v_and_b32_e32 v65, 0xffff0000, v246
	s_waitcnt lgkmcnt(1)
	v_pk_mul_f32 v[54:55], v[44:45], v[44:45]
	v_pk_mul_f32 v[56:57], v[42:43], v[42:43]
	s_nop 0
	v_pk_mov_b32 v[58:59], v[56:57], v[54:55] op_sel:[1,0]
	v_mov_b32_e32 v57, v55
	v_pk_add_f32 v[54:55], v[58:59], v[56:57]
	s_waitcnt lgkmcnt(0)
	v_pk_mul_f32 v[56:57], v[48:49], v[48:49]
	v_pk_mul_f32 v[58:59], v[46:47], v[46:47]
	v_mov_b32_e32 v60, v56
	v_mov_b32_e32 v61, v58
	v_mov_b32_e32 v58, v57
	v_pk_add_f32 v[56:57], v[60:61], v[58:59]
	v_add_f32_e32 v54, v54, v55
	v_add_f32_e32 v54, v54, v57
	v_add_f32_e32 v54, v56, v54
	s_nop 1
	v_add_f32_dpp v54, v54, v54 quad_perm:[1,0,3,2] row_mask:0xf bank_mask:0xf
	s_nop 1
	v_add_f32_dpp v54, v54, v54 quad_perm:[2,3,0,1] row_mask:0xf bank_mask:0xf
	s_nop 1
	v_add_f32_dpp v62, v54, v54 row_half_mirror row_mask:0xf bank_mask:0xf
	s_nop 1
	v_add_f32_dpp v62, v62, v62 row_mirror row_mask:0xf bank_mask:0xf
	v_fmamk_f32 v62, v62, 0x3c000000, v118
	v_rsq_f32_e32 v62, v62
	s_nop 0
	v_pk_mul_f32 v[46:47], v[46:47], v[62:63] op_sel_hi:[1,0]
	v_pk_mul_f32 v[48:49], v[48:49], v[62:63] op_sel_hi:[1,0]
	v_pk_mul_f32 v[42:43], v[42:43], v[62:63] op_sel_hi:[1,0]
	v_pk_mul_f32 v[44:45], v[44:45], v[62:63] op_sel_hi:[1,0]
	s_waitcnt vmcnt(1)
	v_pk_mul_f32 v[42:43], v[232:233], v[42:43]
	v_pk_mul_f32 v[46:47], v[236:237], v[46:47]
	v_lshlrev_b32_e32 v58, 16, v247
	v_and_b32_e32 v59, 0xffff0000, v247
	v_pk_mul_f32 v[48:49], v[238:239], v[48:49]
	v_lshlrev_b32_e32 v54, 16, v245
	v_pk_mul_f32 v[48:49], v[48:49], v[58:59]
	v_lshlrev_b32_e32 v58, 16, v244
	v_and_b32_e32 v59, 0xffff0000, v244
	v_and_b32_e32 v55, 0xffff0000, v245
	v_pk_mul_f32 v[44:45], v[234:235], v[44:45]
	v_pk_mul_f32 v[46:47], v[46:47], v[64:65]
	v_pk_mul_f32 v[42:43], v[42:43], v[58:59]
	v_pk_mul_f32 v[44:45], v[44:45], v[54:55]
	v_cvt_pk_bf16_f32 v42, v42, v43
	v_cvt_pk_bf16_f32 v43, v44, v45
	v_cvt_pk_bf16_f32 v44, v46, v47
	v_cvt_pk_bf16_f32 v45, v48, v49
	global_store_dwordx4 v[102:103], v[42:45], off offset:1536
	ds_read_b128 v[42:45], v119
	ds_read_b128 v[46:49], v119 offset:16
	s_waitcnt vmcnt(1)
	v_lshlrev_b32_e32 v64, 16, v52
	v_and_b32_e32 v65, 0xffff0000, v52
	v_lshlrev_b32_e32 v52, 16, v53
	s_waitcnt lgkmcnt(1)
	v_pk_mul_f32 v[54:55], v[44:45], v[44:45]
	v_pk_mul_f32 v[56:57], v[42:43], v[42:43]
	v_and_b32_e32 v53, 0xffff0000, v53
	v_pk_mov_b32 v[58:59], v[56:57], v[54:55] op_sel:[1,0]
	v_mov_b32_e32 v57, v55
	v_pk_add_f32 v[54:55], v[58:59], v[56:57]
	s_waitcnt lgkmcnt(0)
	v_pk_mul_f32 v[56:57], v[48:49], v[48:49]
	v_pk_mul_f32 v[58:59], v[46:47], v[46:47]
	v_mov_b32_e32 v60, v56
	v_mov_b32_e32 v61, v58
	v_mov_b32_e32 v58, v57
	v_pk_add_f32 v[56:57], v[60:61], v[58:59]
	v_add_f32_e32 v54, v54, v55
	v_add_f32_e32 v54, v54, v57
	v_add_f32_e32 v54, v56, v54
	s_nop 1
	v_add_f32_dpp v54, v54, v54 quad_perm:[1,0,3,2] row_mask:0xf bank_mask:0xf
	s_nop 1
	v_add_f32_dpp v54, v54, v54 quad_perm:[2,3,0,1] row_mask:0xf bank_mask:0xf
	s_nop 1
	v_add_f32_dpp v62, v54, v54 row_half_mirror row_mask:0xf bank_mask:0xf
	s_nop 1
	v_add_f32_dpp v62, v62, v62 row_mirror row_mask:0xf bank_mask:0xf
	v_fmamk_f32 v62, v62, 0x3c000000, v118
	v_rsq_f32_e32 v62, v62
	s_nop 0
	v_pk_mul_f32 v[48:49], v[48:49], v[62:63] op_sel_hi:[1,0]
	v_pk_mul_f32 v[46:47], v[46:47], v[62:63] op_sel_hi:[1,0]
	v_pk_mul_f32 v[42:43], v[42:43], v[62:63] op_sel_hi:[1,0]
	v_pk_mul_f32 v[44:45], v[44:45], v[62:63] op_sel_hi:[1,0]
	v_pk_mul_f32 v[42:43], v[232:233], v[42:43]
	v_pk_mul_f32 v[48:49], v[238:239], v[48:49]
	v_pk_mul_f32 v[46:47], v[236:237], v[46:47]
	v_pk_mul_f32 v[48:49], v[48:49], v[52:53]
	v_lshlrev_b32_e32 v52, 16, v50
	v_and_b32_e32 v53, 0xffff0000, v50
	v_lshlrev_b32_e32 v50, 16, v51
	v_and_b32_e32 v51, 0xffff0000, v51
	v_pk_mul_f32 v[44:45], v[234:235], v[44:45]
	v_pk_mul_f32 v[46:47], v[46:47], v[64:65]
	v_pk_mul_f32 v[42:43], v[42:43], v[52:53]
	v_pk_mul_f32 v[44:45], v[44:45], v[50:51]
	v_cvt_pk_bf16_f32 v42, v42, v43
	v_cvt_pk_bf16_f32 v43, v44, v45
	v_cvt_pk_bf16_f32 v44, v46, v47
	v_cvt_pk_bf16_f32 v45, v48, v49
	global_store_dwordx4 v[100:101], v[42:45], off offset:1536
	s_waitcnt vmcnt(2)
	v_lshl_or_b32 v129, v185, 16, v184
	v_lshl_or_b32 v127, v190, 16, v191
	v_lshl_or_b32 v131, v192, 16, v188
	v_lshl_or_b32 v128, v194, 16, v189
	v_lshl_or_b32 v133, v196, 16, v195
	v_lshl_or_b32 v135, v203, 16, v202
	v_lshl_or_b32 v134, v214, 16, v215
	v_lshl_or_b32 v34, v187, 16, v186
	v_lshl_or_b32 v35, v199, 16, v193
	v_lshl_or_b32 v36, v200, 16, v197
	v_lshl_or_b32 v130, v198, 16, v201
	v_lshl_or_b32 v37, v205, 16, v204
	v_lshl_or_b32 v132, v206, 16, v207
	v_lshl_or_b32 v137, v209, 16, v208
	v_lshl_or_b32 v38, v211, 16, v210
	v_lshl_or_b32 v139, v216, 16, v212
	v_lshl_or_b32 v136, v218, 16, v213
	v_lshl_or_b32 v141, v220, 16, v219
	v_lshl_or_b32 v39, v223, 16, v217
	v_lshl_or_b32 v40, v224, 16, v221
	v_lshl_or_b32 v138, v222, 16, v225
	v_lshl_or_b32 v142, v227, 16, v226
	v_lshl_or_b32 v41, v229, 16, v228
	v_lshl_or_b32 v140, v230, 16, v231
	v_mov_b32_e32 v46, v127
	v_mov_b32_e32 v47, v128
	v_mov_b32_e32 v49, v130
	v_mov_b32_e32 v51, v132
	v_mov_b32_e32 v52, v134
	v_mov_b32_e32 v53, v136
	v_mov_b32_e32 v54, v138
	v_mov_b32_e32 v48, v140
	v_mov_b32_e32 v42, v129
	v_mov_b32_e32 v43, v131
	v_mov_b32_e32 v44, v133
	v_mov_b32_e32 v45, v135
	v_mov_b32_e32 v50, v137
	v_mov_b32_e32 v55, v139
	v_mov_b32_e32 v56, v141
	v_mov_b32_e32 v57, v142
	s_cbranch_scc0 .LBB0_1168
